# attention load balance: workgroup c+128 takes query blocks 1,0 of workgroup c (which also runs a sample-stream task)
# baseline (speedup 1.0000x reference)
; __device__ void phase_attn(KP p, PG8_LAS unsigned char* lds, float* ldsf, int tid_in) {
;     ...
;     constexpr int KS = 104, VS = 72, KB = 64 * KS * 2, VB = 64 * VS * 2, BUF = KB + VB;
;     const bool lo = tid < 256;
;     const int krow = tid >> 3, kch = (tid & 7) * 8;
;     const int rrow = (tid & 255) >> 2, rch = (tid & 3) * 8;
;     const int vdA = lo ? 32 + (tid >> 3) : (tid - 256) >> 3;
;     const unsigned k_st = (unsigned)(krow * KS + kch) * 2u, r_st = (unsigned)(rrow * KS + 64 + rch) * 2u, v_st = (unsigned)KB + (unsigned)(vdA * VS + kch) * 2u;
;     const unsigned ka_rd = (unsigned)(fr * KS + g * 8) * 2u, va_rd = (unsigned)KB + (unsigned)(fr * VS + g * 4) * 2u;
;     for (int bh = blockIdx.x; bh < BATCH * N_HEADS; bh += gridDim.x) {
;         const int b = bh >> 3, h = bh & 7; const size_t kr0 = (size_t)b * SEQ;
;         const bf16_t* KNb = KN + kr0 * 512 + h * 64 + (size_t)krow * 512 + kch;
;         const bf16_t* KRb = KR + kr0 * 32 + (size_t)rrow * 32 + rch;
;         const bf16_t* VTb = VT + (size_t)(h * 64 + vdA) * MA + kr0 + kch;
;     ...
;             const int qw = qb * 8 + (7 - wid), cw = qw >> 1, nt = 4 * qb + 4;
;             const bf16_t* Qw = Q + (kr0 + (size_t)qw * 32) * 768 + h * 96;
.LBB0_507:
	v_readlane_b32 s0, v252, 34
	v_readlane_b32 s1, v252, 35
	s_andn2_b64 vcc, exec, s[0:1]
	s_cbranch_vccnz .LBB0_527
	s_mov_b32 s38, 0
	s_mov_b32 s39, 7
	s_mov_b32 s37, 0
	s_cmp_lg_u32 s52, 0x100
	s_cbranch_scc1 .Lqs_init_done
	s_cmp_lt_u32 s2, 0x80
	s_cselect_b32 s37, 2, 0
.Lqs_init_done:
	v_ashrrev_i32_e32 v4, 3, v128
	v_add_u32_e32 v7, 0xffffff00, v128
	s_movk_i32 s0, 0x100
	v_lshlrev_b32_e32 v1, 3, v128
	v_add_u32_e32 v5, 32, v4
	v_lshrrev_b32_e32 v7, 3, v7
	v_cmp_gt_i32_e64 s[4:5], s0, v128
	s_movk_i32 s0, 0x68
	v_and_b32_e32 v6, 56, v1
	v_bfe_u32 v3, v128, 2, 6
	v_and_b32_e32 v1, 24, v1
	v_cndmask_b32_e64 v127, v7, v5, s[4:5]
	v_mul_lo_u32 v5, v4, s0
	v_add_lshl_u32 v164, v5, v6, 1
	v_mad_u32_u24 v5, v3, s0, v1
	v_mov_b32_e32 v7, 0x80
	s_movk_i32 s0, 0x48
	v_lshl_add_u32 v165, v5, 1, v7
	v_mul_lo_u32 v5, v127, s0
	v_add_lshl_u32 v166, v5, v6, 1
	v_mul_u32_u24_e32 v5, 0x68, v134
	v_add_lshl_u32 v167, v2, v5, 1
	v_mul_u32_u24_e32 v5, 0x48, v134
	v_readlane_b32 s0, v252, 18
	v_add_lshl_u32 v170, v0, v5, 1
	v_ashrrev_i32_e32 v5, 31, v4
	v_lshlrev_b32_e32 v8, 6, v3
	v_readlane_b32 s1, v252, 19
	v_lshlrev_b64 v[94:95], 10, v[4:5]
	v_readlane_b32 s8, v252, 0
	v_lshl_add_u64 v[4:5], s[0:1], 0, v[8:9]
	v_readlane_b32 s0, v253, 26
	v_lshlrev_b32_e32 v8, 1, v1
	v_mov_b32_e32 v1, v9
	v_readlane_b32 s1, v253, 27
	v_mov_b32_e32 v3, v9
	v_readlane_b32 s9, v252, 1
	v_lshl_add_u64 v[0:1], v[0:1], 1, s[0:1]
	v_mov_b32_e32 v131, v9
	v_lshl_add_u64 v[96:97], v[4:5], 0, v[8:9]
	v_lshl_add_u64 v[2:3], v[2:3], 1, s[8:9]
	v_lshl_add_u64 v[98:99], v[0:1], 0, v[130:131]
	v_lshlrev_b32_e32 v8, 1, v132
	v_lshlrev_b32_e32 v0, 4, v128
	v_readlane_b32 s0, v254, 13
	v_lshl_add_u64 v[100:101], v[2:3], 0, v[8:9]
	v_and_b32_e32 v8, 0x70, v0
	v_readlane_b32 s1, v254, 14
	v_readlane_b32 s10, v252, 2
	v_readlane_b32 s11, v252, 3
	v_lshl_add_u64 v[102:103], s[0:1], 0, v[8:9]
	v_readlane_b32 s0, v254, 15
	v_or_b32_e32 v0, v94, v8
	v_mov_b32_e32 v1, v95
	v_readlane_b32 s1, v254, 16
	v_lshlrev_b32_e32 v106, 1, v6
	s_mov_b32 s10, s2
	v_lshl_add_u64 v[104:105], s[0:1], 0, v[0:1]
	s_mov_b32 s11, s2
	s_branch .LBB0_510
.LBB0_509:
	s_cmp_lg_u32 s52, 0x100
	s_cbranch_scc1 .Lqs_bh_orig
	s_cmp_lg_u32 s38, 0
	s_cbranch_scc1 .LBB0_527
	s_cmp_lt_u32 s2, 0x80
	s_cbranch_scc1 .LBB0_527
	s_mov_b32 s38, 1
	s_sub_i32 s10, s2, 0x80
	s_mov_b32 s11, s10
	s_mov_b32 s39, 1
	s_mov_b32 s37, 0
	s_branch .LBB0_510

; __device__ __forceinline__ unsigned cvt_pk_bf16(float lo, float hi) { const f32x2c v = {lo, hi}; const bf16x2c b = __builtin_convertvector(v, bf16x2c); return __builtin_bit_cast(unsigned, b); }
; __device__ __forceinline__ float shx(float v, int o, int lane) { return __int_as_float(__builtin_amdgcn_ds_bpermute((lane ^ o) << 2, __float_as_int(v))); }
; __device__ void phase_attn(KP p, PG8_LAS unsigned char* lds, float* ldsf, int tid_in) {
;     ...
;         const int b = bh >> 3, h = bh & 7; const size_t kr0 = (size_t)b * SEQ;
;         const bf16_t* KNb = KN + kr0 * 512 + h * 64 + (size_t)krow * 512 + kch;
;         const bf16_t* KRb = KR + kr0 * 32 + (size_t)rrow * 32 + rch;
;         const bf16_t* VTb = VT + (size_t)(h * 64 + vdA) * MA + kr0 + kch;
;     ...
;             const int qw = qb * 8 + (7 - wid), cw = qw >> 1, nt = 4 * qb + 4;
;             const bf16_t* Qw = Q + (kr0 + (size_t)qw * 32) * 768 + h * 96;
;     ...
;             bf16_t* Ow = O + (kr0 + (size_t)qw * 32) * 512 + h * 64;
; #pragma unroll
;             for (int nb = 0; nb < 2; ++nb) {
;                 float ls = lrun[nb]; ls += shx(ls, 16, lane); ls += shx(ls, 32, lane);
;                 const float inv = 1.f / ls;
; #pragma unroll
;                 for (int df = 0; df < 4; ++df) {
;                     u32x2 t; t[0] = cvt_pk_bf16(o[df][nb][0] * inv, o[df][nb][1] * inv); t[1] = cvt_pk_bf16(o[df][nb][2] * inv, o[df][nb][3] * inv);
;                     *(u32x2*)(Ow + (size_t)(nb * 16 + fr) * 512 + df * 16 + g * 4) = t;
;                 }
;             }
.LBB0_510:
	s_and_b32 s0, s10, 7
	v_lshl_add_u32 v6, s0, 6, v127
	s_lshl_b32 s14, s0, 7
	s_ashr_i32 s0, s11, 3
	s_ashr_i32 s1, s0, 31
	s_and_b32 s15, s11, 7
	s_lshl_b64 s[6:7], s[0:1], 11
	s_lshl_b64 s[8:9], s[0:1], 21
	v_readlane_b32 s12, v252, 24
	v_readlane_b32 s13, v252, 25
	s_add_u32 s12, s12, s8
	s_addc_u32 s13, s13, s9
	s_lshl_b32 s40, s15, 7
	s_add_u32 s12, s12, s40
	s_addc_u32 s13, s13, 0
	v_lshl_add_u64 v[4:5], s[12:13], 0, v[94:95]
	s_lshl_b64 s[12:13], s[0:1], 17
	v_lshl_add_u64 v[110:111], v[96:97], 0, s[12:13]
	v_readlane_b32 s12, v252, 28
	v_mov_b32_e32 v107, v9
	v_readlane_b32 s13, v252, 29
	v_lshl_add_u64 v[108:109], v[4:5], 0, v[106:107]
	v_lshl_add_u32 v7, s15, 6, v127
	v_mov_b64_e32 v[4:5], s[12:13]
	s_mov_b32 s16, 0x30800
	v_mad_i64_i32 v[4:5], s[12:13], v7, s16, v[4:5]
	s_lshl_b64 s[0:1], s[0:1], 12
	v_lshl_add_u64 v[4:5], v[4:5], 0, s[0:1]
	v_lshl_add_u64 v[112:113], v[4:5], 0, v[106:107]
	v_mov_b64_e32 v[4:5], s[0:1]
	v_lshl_add_u64 v[114:115], v[98:99], 0, s[40:41]
	s_mul_i32 s40, s15, 0xc0
	v_mad_i64_i32 v[4:5], s[0:1], v6, s16, v[4:5]
	s_or_b32 s8, s8, s14
	v_lshl_add_u64 v[116:117], v[100:101], 0, s[40:41]
	v_lshl_add_u64 v[118:119], v[102:103], 0, v[4:5]
	v_lshl_add_u64 v[120:121], v[104:105], 0, s[8:9]
	s_lshl_b32 s0, s39, 2
	s_add_i32 s0, s0, 4
	s_add_i32 s1, s0, -1
	v_mov_b32_e32 v107, s39
	s_mov_b32 s36, s39
	s_branch .LBB0_512
.LBB0_511:
	s_or_b64 exec, exec, s[8:9]
	ds_bpermute_b32 v8, v168, v125
	v_lshlrev_b64 v[22:23], 10, v[122:123]
	v_lshl_add_u64 v[22:23], v[114:115], 0, v[22:23]
	s_waitcnt lgkmcnt(0)
	s_barrier
	v_add_f32_e32 v8, v125, v8
	ds_bpermute_b32 v24, v169, v8
	s_waitcnt lgkmcnt(0)
	s_add_i32 s0, s0, -4
	s_add_i32 s1, s1, -4
	v_add_f32_e32 v8, v8, v24
	v_div_scale_f32 v24, s[8:9], v8, v8, 1.0
	v_rcp_f32_e32 v25, v24
	v_div_scale_f32 v26, vcc, 1.0, v8, 1.0
	v_fma_f32 v27, -v24, v25, 1.0
	v_fmac_f32_e32 v25, v27, v25
	v_mul_f32_e32 v27, v26, v25
	v_fma_f32 v28, -v24, v27, v26
	v_fmac_f32_e32 v27, v28, v25
	ds_bpermute_b32 v28, v168, v124
	v_fma_f32 v24, -v24, v27, v26
	v_div_fmas_f32 v24, v24, v25, v27
	v_div_fixup_f32 v8, v24, v8, 1.0
	v_pk_mul_f32 v[24:25], v[54:55], v[8:9] op_sel_hi:[1,0]
	s_waitcnt lgkmcnt(0)
	v_add_f32_e32 v28, v124, v28
	ds_bpermute_b32 v29, v169, v28
	v_pk_mul_f32 v[26:27], v[56:57], v[8:9] op_sel_hi:[1,0]
	v_cvt_pk_bf16_f32 v24, v24, v25
	v_cvt_pk_bf16_f32 v25, v26, v27
	global_store_dwordx2 v[22:23], v[24:25], off
	s_waitcnt lgkmcnt(0)
	v_add_f32_e32 v28, v28, v29
	v_div_scale_f32 v29, s[8:9], v28, v28, 1.0
	v_pk_mul_f32 v[24:25], v[58:59], v[8:9] op_sel_hi:[1,0]
	v_pk_mul_f32 v[26:27], v[60:61], v[8:9] op_sel_hi:[1,0]
	v_rcp_f32_e32 v30, v29
	v_cvt_pk_bf16_f32 v24, v24, v25
	v_cvt_pk_bf16_f32 v25, v26, v27
	global_store_dwordx2 v[22:23], v[24:25], off offset:32
	v_pk_mul_f32 v[24:25], v[62:63], v[8:9] op_sel_hi:[1,0]
	v_pk_mul_f32 v[26:27], v[64:65], v[8:9] op_sel_hi:[1,0]
	v_cvt_pk_bf16_f32 v24, v24, v25
	v_cvt_pk_bf16_f32 v25, v26, v27
	global_store_dwordx2 v[22:23], v[24:25], off offset:64
	v_pk_mul_f32 v[24:25], v[66:67], v[8:9] op_sel_hi:[1,0]
	v_pk_mul_f32 v[26:27], v[68:69], v[8:9] op_sel_hi:[1,0]
	v_fma_f32 v8, -v29, v30, 1.0
	v_cvt_pk_bf16_f32 v24, v24, v25
	v_cvt_pk_bf16_f32 v25, v26, v27
	v_fmac_f32_e32 v30, v8, v30
	v_div_scale_f32 v8, vcc, 1.0, v28, 1.0
	global_store_dwordx2 v[22:23], v[24:25], off offset:96
	v_mul_f32_e32 v24, v8, v30
	v_fma_f32 v25, -v29, v24, v8
	v_fmac_f32_e32 v24, v25, v30
	v_fma_f32 v8, -v29, v24, v8
	v_div_fmas_f32 v8, v8, v30, v24
	v_div_fixup_f32 v8, v8, v28, 1.0
	v_pk_mul_f32 v[4:5], v[4:5], v[8:9] op_sel_hi:[1,0]
	v_pk_mul_f32 v[6:7], v[6:7], v[8:9] op_sel_hi:[1,0]
	s_movk_i32 s8, 0x4000
	v_cvt_pk_bf16_f32 v4, v4, v5
	v_cvt_pk_bf16_f32 v5, v6, v7
	v_add_co_u32_e32 v6, vcc, s8, v22
	s_nop 1
	v_addc_co_u32_e32 v7, vcc, 0, v23, vcc
	global_store_dwordx2 v[6:7], v[4:5], off
	v_pk_mul_f32 v[4:5], v[10:11], v[8:9] op_sel_hi:[1,0]
	v_pk_mul_f32 v[10:11], v[12:13], v[8:9] op_sel_hi:[1,0]
	v_cvt_pk_bf16_f32 v4, v4, v5
	v_cvt_pk_bf16_f32 v5, v10, v11
	global_store_dwordx2 v[6:7], v[4:5], off offset:32
	v_pk_mul_f32 v[4:5], v[14:15], v[8:9] op_sel_hi:[1,0]
	v_pk_mul_f32 v[10:11], v[16:17], v[8:9] op_sel_hi:[1,0]
	v_cvt_pk_bf16_f32 v4, v4, v5
	v_cvt_pk_bf16_f32 v5, v10, v11
	global_store_dwordx2 v[6:7], v[4:5], off offset:64
	v_pk_mul_f32 v[4:5], v[18:19], v[8:9] op_sel_hi:[1,0]
	v_pk_mul_f32 v[10:11], v[20:21], v[8:9] op_sel_hi:[1,0]
	v_subrev_co_u32_e32 v107, vcc, 1, v107
	v_cvt_pk_bf16_f32 v4, v4, v5
	v_cvt_pk_bf16_f32 v5, v10, v11
	s_sub_i32 s36, s36, 1
	global_store_dwordx2 v[6:7], v[4:5], off offset:96
	s_cmp_lt_i32 s36, s37
	s_cbranch_scc1 .LBB0_509
